# SwiGLU epilogue: silu division via v_rcp_f32*mul (f32) instead of the IEEE division expansion; helper instructions removed
# baseline (speedup 1.0000x reference)
.LBB0_686:
	s_or_b64 exec, exec, s[38:39]
	v_mul_f32_e32 v131, 0xbfb8aa3b, v124
	v_exp_f32_e32 v132, v131
	v_mul_f32_e32 v131, 0xbfb8aa3b, v125
	v_exp_f32_e32 v133, v131
	v_or_b32_e32 v130, s30, v146
	s_lshl_b32 s38, s56, 7
	v_lshlrev_b32_e32 v131, 4, v145
	v_pk_add_f32 v[132:133], v[132:133], 1.0 op_sel_hi:[1,0]
	v_lshlrev_b32_e32 v134, 2, v144
	v_or3_b32 v134, v131, s38, v134
	v_add_u32_e32 v130, v130, v147
	v_ashrrev_i32_e32 v135, 31, v134
	v_div_scale_f32 v139, s[30:31], v132, v132, v124
	v_rcp_f32_e32 v140, v139
	v_rcp_f32_e32 v131, v133
	s_nop 0
	v_mul_f32_e32 v125, v125, v131
	v_fma_f32 v131, -v139, v140, 1.0
	v_fmac_f32_e32 v140, v131, v140
	v_mul_f32_e32 v136, 0xbfb8aa3b, v126
	v_mul_f32_e32 v137, 0xbfb8aa3b, v127
	v_exp_f32_e32 v136, v136
	v_exp_f32_e32 v137, v137
	v_rcp_f32_e32 v131, v132
	s_nop 0
	v_mul_f32_e32 v124, v124, v131
	v_pk_add_f32 v[136:137], v[136:137], 1.0 op_sel_hi:[1,0]
	v_pk_mul_f32 v[120:121], v[120:121], v[124:125]
	v_div_scale_f32 v133, s[30:31], v137, v137, v127
	v_rcp_f32_e32 v138, v133
	v_cvt_pk_bf16_f32 v132, v120, v121
	v_fma_f32 v120, -v133, v138, 1.0
	v_fmac_f32_e32 v138, v120, v138
	v_div_scale_f32 v124, s[30:31], v136, v136, v126
	v_rcp_f32_e32 v120, v137
	s_nop 0
	v_mul_f32_e32 v121, v127, v120
	v_rcp_f32_e32 v120, v136
	s_nop 0
	v_mul_f32_e32 v120, v126, v120
	v_pk_mul_f32 v[120:121], v[122:123], v[120:121]
	v_lshlrev_b64 v[122:123], 1, v[134:135]
	v_cvt_pk_bf16_f32 v133, v120, v121
	v_mov_b64_e32 v[120:121], s[6:7]
	v_mad_i64_i32 v[124:125], s[30:31], v130, s53, v[120:121]
	v_lshl_add_u64 v[124:125], v[124:125], 0, v[122:123]
	flat_store_dwordx2 v[124:125], v[132:133]
	v_mul_f32_e32 v126, 0xbfb8aa3b, v116
	v_mul_f32_e32 v127, 0xbfb8aa3b, v117
	v_exp_f32_e32 v126, v126
	v_exp_f32_e32 v127, v127
	v_or_b32_e32 v134, 16, v130
	v_pk_add_f32 v[126:127], v[126:127], 1.0 op_sel_hi:[1,0]
	s_nop 0
	v_div_scale_f32 v136, s[30:31], v126, v126, v116
	v_rcp_f32_e32 v137, v136
	v_rcp_f32_e32 v131, v127
	s_nop 0
	v_mul_f32_e32 v117, v117, v131
	v_fma_f32 v127, -v136, v137, 1.0
	v_fmac_f32_e32 v137, v127, v137
	v_mul_f32_e32 v132, 0xbfb8aa3b, v118
	v_mul_f32_e32 v133, 0xbfb8aa3b, v119
	v_exp_f32_e32 v132, v132
	v_exp_f32_e32 v133, v133
	v_rcp_f32_e32 v127, v126
	s_nop 0
	v_mul_f32_e32 v116, v116, v127
	v_pk_add_f32 v[132:133], v[132:133], 1.0 op_sel_hi:[1,0]
	v_pk_mul_f32 v[112:113], v[112:113], v[116:117]
	v_div_scale_f32 v131, s[30:31], v133, v133, v119
	v_rcp_f32_e32 v135, v131
	v_cvt_pk_bf16_f32 v116, v112, v113
	v_fma_f32 v112, -v131, v135, 1.0
	v_fmac_f32_e32 v135, v112, v135
	v_div_scale_f32 v117, s[30:31], v132, v132, v118
	v_rcp_f32_e32 v112, v133
	s_nop 0
	v_mul_f32_e32 v113, v119, v112
	v_rcp_f32_e32 v112, v132
	s_nop 0
	v_mul_f32_e32 v112, v118, v112
	v_pk_mul_f32 v[112:113], v[114:115], v[112:113]
	s_nop 0
	v_cvt_pk_bf16_f32 v117, v112, v113
	v_mad_i64_i32 v[112:113], s[30:31], v134, s53, v[120:121]
	v_lshl_add_u64 v[112:113], v[112:113], 0, v[122:123]
	flat_store_dwordx2 v[112:113], v[116:117]
	v_mul_f32_e32 v114, 0xbfb8aa3b, v108
	v_mul_f32_e32 v115, 0xbfb8aa3b, v109
	v_exp_f32_e32 v114, v114
	v_exp_f32_e32 v115, v115
	v_or_b32_e32 v118, 32, v130
	v_pk_add_f32 v[114:115], v[114:115], 1.0 op_sel_hi:[1,0]
	s_nop 0
	v_div_scale_f32 v119, s[30:31], v114, v114, v108
	v_rcp_f32_e32 v127, v119
	v_rcp_f32_e32 v116, v115
	s_nop 0
	v_mul_f32_e32 v109, v109, v116
	v_mul_f32_e32 v117, 0xbfb8aa3b, v111
	v_fma_f32 v115, -v119, v127, 1.0
	v_fmac_f32_e32 v127, v115, v127
	v_mul_f32_e32 v116, 0xbfb8aa3b, v110
	v_exp_f32_e32 v116, v116
	v_exp_f32_e32 v117, v117
	v_rcp_f32_e32 v115, v114
	s_nop 0
	v_mul_f32_e32 v108, v108, v115
	v_pk_add_f32 v[116:117], v[116:117], 1.0 op_sel_hi:[1,0]
	v_pk_mul_f32 v[104:105], v[104:105], v[108:109]
	v_div_scale_f32 v119, s[30:31], v117, v117, v111
	v_rcp_f32_e32 v126, v119
	v_cvt_pk_bf16_f32 v108, v104, v105
	v_fma_f32 v104, -v119, v126, 1.0
	v_fmac_f32_e32 v126, v104, v126
	v_div_scale_f32 v109, s[30:31], v116, v116, v110
	v_rcp_f32_e32 v104, v117
	s_nop 0
	v_mul_f32_e32 v105, v111, v104
	v_rcp_f32_e32 v104, v116
	s_nop 0
	v_mul_f32_e32 v104, v110, v104
	v_pk_mul_f32 v[104:105], v[106:107], v[104:105]
	s_nop 0
	v_cvt_pk_bf16_f32 v109, v104, v105
	v_mad_i64_i32 v[104:105], s[30:31], v118, s53, v[120:121]
	v_lshl_add_u64 v[104:105], v[104:105], 0, v[122:123]
	flat_store_dwordx2 v[104:105], v[108:109]
	v_mul_f32_e32 v106, 0xbfb8aa3b, v100
	v_mul_f32_e32 v107, 0xbfb8aa3b, v101
	v_exp_f32_e32 v106, v106
	v_exp_f32_e32 v107, v107
	v_or_b32_e32 v110, 48, v130
	v_pk_add_f32 v[106:107], v[106:107], 1.0 op_sel_hi:[1,0]
	s_nop 0
	v_div_scale_f32 v111, s[30:31], v106, v106, v100
	v_rcp_f32_e32 v115, v111
	v_rcp_f32_e32 v108, v107
	s_nop 0
	v_mul_f32_e32 v101, v101, v108
	v_mul_f32_e32 v109, 0xbfb8aa3b, v103
	v_fma_f32 v107, -v111, v115, 1.0
	v_fmac_f32_e32 v115, v107, v115
	v_mul_f32_e32 v108, 0xbfb8aa3b, v102
	v_exp_f32_e32 v108, v108
	v_exp_f32_e32 v109, v109
	v_rcp_f32_e32 v107, v106
	s_nop 0
	v_mul_f32_e32 v100, v100, v107
	v_pk_add_f32 v[108:109], v[108:109], 1.0 op_sel_hi:[1,0]
	v_pk_mul_f32 v[96:97], v[96:97], v[100:101]
	v_div_scale_f32 v111, s[30:31], v109, v109, v103
	v_rcp_f32_e32 v114, v111
	v_cvt_pk_bf16_f32 v100, v96, v97
	v_fma_f32 v96, -v111, v114, 1.0
	v_fmac_f32_e32 v114, v96, v114
	v_div_scale_f32 v101, s[30:31], v108, v108, v102
	v_rcp_f32_e32 v106, v101
	v_rcp_f32_e32 v96, v109
	s_nop 0
	v_mul_f32_e32 v97, v103, v96
	v_fma_f32 v96, -v101, v106, 1.0
	v_fmac_f32_e32 v106, v96, v106
	v_div_scale_f32 v96, vcc, v102, v108, v102
	v_mul_f32_e32 v103, v96, v106
	v_fma_f32 v107, -v101, v103, v96
	v_rcp_f32_e32 v96, v108
	s_nop 0
	v_mul_f32_e32 v96, v102, v96
	v_pk_mul_f32 v[96:97], v[98:99], v[96:97]
	s_nop 0
	v_cvt_pk_bf16_f32 v101, v96, v97
	v_mad_i64_i32 v[96:97], s[30:31], v110, s53, v[120:121]
	v_lshl_add_u64 v[96:97], v[96:97], 0, v[122:123]
	flat_store_dwordx2 v[96:97], v[100:101]
	v_mul_f32_e32 v98, 0xbfb8aa3b, v92
	v_mul_f32_e32 v99, 0xbfb8aa3b, v93
	v_exp_f32_e32 v98, v98
	v_exp_f32_e32 v99, v99
	s_nop 0
	v_pk_add_f32 v[98:99], v[98:99], 1.0 op_sel_hi:[1,0]
	s_nop 0
	v_div_scale_f32 v102, s[30:31], v98, v98, v92
	v_rcp_f32_e32 v106, v102
	v_rcp_f32_e32 v100, v99
	s_nop 0
	v_mul_f32_e32 v93, v93, v100
	v_mul_f32_e32 v101, 0xbfb8aa3b, v95
	v_fma_f32 v99, -v102, v106, 1.0
	v_fmac_f32_e32 v106, v99, v106
	v_mul_f32_e32 v100, 0xbfb8aa3b, v94
	v_exp_f32_e32 v100, v100
	v_exp_f32_e32 v101, v101
	v_rcp_f32_e32 v99, v98
	s_nop 0
	v_mul_f32_e32 v92, v92, v99
	v_pk_add_f32 v[100:101], v[100:101], 1.0 op_sel_hi:[1,0]
	v_pk_mul_f32 v[88:89], v[88:89], v[92:93]
	v_div_scale_f32 v102, s[30:31], v101, v101, v95
	v_rcp_f32_e32 v103, v102
	v_cvt_pk_bf16_f32 v88, v88, v89
	v_div_scale_f32 v98, s[30:31], v100, v100, v94
	v_fma_f32 v89, -v102, v103, 1.0
	v_fmac_f32_e32 v103, v89, v103
	v_rcp_f32_e32 v99, v98
	v_rcp_f32_e32 v89, v101
	s_nop 0
	v_mul_f32_e32 v93, v95, v89
	v_fma_f32 v89, -v98, v99, 1.0
	v_fmac_f32_e32 v99, v89, v99
	v_div_scale_f32 v89, vcc, v94, v100, v94
	v_mul_f32_e32 v92, v89, v99
	v_fma_f32 v95, -v98, v92, v89
	v_rcp_f32_e32 v89, v100
	s_nop 0
	v_mul_f32_e32 v92, v94, v89
	v_pk_mul_f32 v[90:91], v[90:91], v[92:93]
	s_nop 0
	v_cvt_pk_bf16_f32 v89, v90, v91
	flat_store_dwordx2 v[124:125], v[88:89] offset:128
	v_mul_f32_e32 v88, 0xbfb8aa3b, v84
	v_mul_f32_e32 v89, 0xbfb8aa3b, v85
	v_exp_f32_e32 v88, v88
	v_exp_f32_e32 v89, v89
	s_nop 0
	v_pk_add_f32 v[88:89], v[88:89], 1.0 op_sel_hi:[1,0]
	s_nop 0
	v_div_scale_f32 v92, s[30:31], v88, v88, v84
	v_rcp_f32_e32 v94, v92
	v_rcp_f32_e32 v90, v89
	s_nop 0
	v_mul_f32_e32 v85, v85, v90
	v_mul_f32_e32 v91, 0xbfb8aa3b, v87
	v_fma_f32 v89, -v92, v94, 1.0
	v_fmac_f32_e32 v94, v89, v94
	v_mul_f32_e32 v90, 0xbfb8aa3b, v86
	v_exp_f32_e32 v90, v90
	v_exp_f32_e32 v91, v91
	v_rcp_f32_e32 v89, v88
	s_nop 0
	v_mul_f32_e32 v84, v84, v89
	v_pk_add_f32 v[90:91], v[90:91], 1.0 op_sel_hi:[1,0]
	v_pk_mul_f32 v[80:81], v[80:81], v[84:85]
	v_div_scale_f32 v92, s[30:31], v91, v91, v87
	v_rcp_f32_e32 v93, v92
	v_cvt_pk_bf16_f32 v80, v80, v81
	v_div_scale_f32 v88, s[30:31], v90, v90, v86
	v_fma_f32 v81, -v92, v93, 1.0
	v_fmac_f32_e32 v93, v81, v93
	v_rcp_f32_e32 v89, v88
	v_rcp_f32_e32 v81, v91
	s_nop 0
	v_mul_f32_e32 v85, v87, v81
	v_fma_f32 v81, -v88, v89, 1.0
	v_fmac_f32_e32 v89, v81, v89
	v_div_scale_f32 v81, vcc, v86, v90, v86
	v_mul_f32_e32 v84, v81, v89
	v_fma_f32 v87, -v88, v84, v81
	v_rcp_f32_e32 v81, v90
	s_nop 0
	v_mul_f32_e32 v84, v86, v81
	v_pk_mul_f32 v[82:83], v[82:83], v[84:85]
	s_nop 0
	v_cvt_pk_bf16_f32 v81, v82, v83
	flat_store_dwordx2 v[112:113], v[80:81] offset:128
	v_mul_f32_e32 v80, 0xbfb8aa3b, v76
	v_mul_f32_e32 v81, 0xbfb8aa3b, v77
	v_exp_f32_e32 v80, v80
	v_exp_f32_e32 v81, v81
	s_nop 0
	v_pk_add_f32 v[80:81], v[80:81], 1.0 op_sel_hi:[1,0]
	s_nop 0
	v_div_scale_f32 v84, s[30:31], v80, v80, v76
	v_rcp_f32_e32 v86, v84
	v_rcp_f32_e32 v82, v81
	s_nop 0
	v_mul_f32_e32 v77, v77, v82
	v_mul_f32_e32 v83, 0xbfb8aa3b, v79
	v_fma_f32 v81, -v84, v86, 1.0
	v_fmac_f32_e32 v86, v81, v86
	v_mul_f32_e32 v82, 0xbfb8aa3b, v78
	v_exp_f32_e32 v82, v82
	v_exp_f32_e32 v83, v83
	v_rcp_f32_e32 v81, v80
	s_nop 0
	v_mul_f32_e32 v76, v76, v81
	v_pk_add_f32 v[82:83], v[82:83], 1.0 op_sel_hi:[1,0]
	v_pk_mul_f32 v[72:73], v[72:73], v[76:77]
	v_div_scale_f32 v84, s[30:31], v83, v83, v79
	v_rcp_f32_e32 v85, v84
	v_cvt_pk_bf16_f32 v72, v72, v73
	v_div_scale_f32 v80, s[30:31], v82, v82, v78
	v_fma_f32 v73, -v84, v85, 1.0
	v_fmac_f32_e32 v85, v73, v85
	v_rcp_f32_e32 v81, v80
	v_rcp_f32_e32 v73, v83
	s_nop 0
	v_mul_f32_e32 v77, v79, v73
	v_fma_f32 v73, -v80, v81, 1.0
	v_fmac_f32_e32 v81, v73, v81
	v_div_scale_f32 v73, vcc, v78, v82, v78
	v_mul_f32_e32 v76, v73, v81
	v_fma_f32 v79, -v80, v76, v73
	v_rcp_f32_e32 v73, v82
	s_nop 0
	v_mul_f32_e32 v76, v78, v73
	v_pk_mul_f32 v[74:75], v[74:75], v[76:77]
	s_nop 0
	v_cvt_pk_bf16_f32 v73, v74, v75
	flat_store_dwordx2 v[104:105], v[72:73] offset:128
	v_mul_f32_e32 v72, 0xbfb8aa3b, v68
	v_mul_f32_e32 v73, 0xbfb8aa3b, v69
	v_exp_f32_e32 v72, v72
	v_exp_f32_e32 v73, v73
	s_nop 0
	v_pk_add_f32 v[72:73], v[72:73], 1.0 op_sel_hi:[1,0]
	s_nop 0
	v_div_scale_f32 v76, s[30:31], v72, v72, v68
	v_rcp_f32_e32 v78, v76
	v_rcp_f32_e32 v74, v73
	s_nop 0
	v_mul_f32_e32 v69, v69, v74
	v_mul_f32_e32 v75, 0xbfb8aa3b, v71
	v_fma_f32 v73, -v76, v78, 1.0
	v_fmac_f32_e32 v78, v73, v78
	v_mul_f32_e32 v74, 0xbfb8aa3b, v70
	v_exp_f32_e32 v74, v74
	v_exp_f32_e32 v75, v75
	v_rcp_f32_e32 v73, v72
	s_nop 0
	v_mul_f32_e32 v68, v68, v73
	v_pk_add_f32 v[74:75], v[74:75], 1.0 op_sel_hi:[1,0]
	v_pk_mul_f32 v[64:65], v[64:65], v[68:69]
	v_div_scale_f32 v76, s[30:31], v75, v75, v71
	v_rcp_f32_e32 v77, v76
	v_cvt_pk_bf16_f32 v64, v64, v65
	v_div_scale_f32 v72, s[30:31], v74, v74, v70
	v_fma_f32 v65, -v76, v77, 1.0
	v_fmac_f32_e32 v77, v65, v77
	v_rcp_f32_e32 v73, v72
	v_rcp_f32_e32 v65, v75
	s_nop 0
	v_mul_f32_e32 v69, v71, v65
	v_fma_f32 v65, -v72, v73, 1.0
	v_fmac_f32_e32 v73, v65, v73
	v_rcp_f32_e32 v65, v74
	s_nop 0
	v_mul_f32_e32 v68, v70, v65
	v_pk_mul_f32 v[66:67], v[66:67], v[68:69]
	s_nop 0
	v_cvt_pk_bf16_f32 v65, v66, v67
	flat_store_dwordx2 v[96:97], v[64:65] offset:128
	v_mul_f32_e32 v64, 0xbfb8aa3b, v60
	v_mul_f32_e32 v65, 0xbfb8aa3b, v61
	v_exp_f32_e32 v64, v64
	v_exp_f32_e32 v65, v65
	v_add_u32_e32 v68, 0x80, v130
	v_pk_add_f32 v[64:65], v[64:65], 1.0 op_sel_hi:[1,0]
	s_nop 0
	v_div_scale_f32 v69, s[30:31], v64, v64, v60
	v_rcp_f32_e32 v71, v69
	v_rcp_f32_e32 v66, v65
	s_nop 0
	v_mul_f32_e32 v61, v61, v66
	v_mul_f32_e32 v67, 0xbfb8aa3b, v63
	v_fma_f32 v65, -v69, v71, 1.0
	v_fmac_f32_e32 v71, v65, v71
	v_mul_f32_e32 v66, 0xbfb8aa3b, v62
	v_exp_f32_e32 v66, v66
	v_exp_f32_e32 v67, v67
	v_rcp_f32_e32 v65, v64
	s_nop 0
	v_mul_f32_e32 v60, v60, v65
	v_pk_add_f32 v[66:67], v[66:67], 1.0 op_sel_hi:[1,0]
	v_pk_mul_f32 v[56:57], v[56:57], v[60:61]
	v_div_scale_f32 v69, s[30:31], v67, v67, v63
	v_rcp_f32_e32 v70, v69
	v_cvt_pk_bf16_f32 v60, v56, v57
	v_fma_f32 v56, -v69, v70, 1.0
	v_fmac_f32_e32 v70, v56, v70
	v_div_scale_f32 v61, s[30:31], v66, v66, v62
	v_rcp_f32_e32 v56, v67
	s_nop 0
	v_mul_f32_e32 v57, v63, v56
	v_rcp_f32_e32 v56, v66
	s_nop 0
	v_mul_f32_e32 v56, v62, v56
	v_pk_mul_f32 v[56:57], v[58:59], v[56:57]
	s_nop 0
	v_cvt_pk_bf16_f32 v61, v56, v57
	v_mad_i64_i32 v[56:57], s[30:31], v68, s53, v[120:121]
	v_lshl_add_u64 v[56:57], v[56:57], 0, v[122:123]
	flat_store_dwordx2 v[56:57], v[60:61]
	v_mul_f32_e32 v58, 0xbfb8aa3b, v52
	v_mul_f32_e32 v59, 0xbfb8aa3b, v53
	v_exp_f32_e32 v58, v58
	v_exp_f32_e32 v59, v59
	v_add_u32_e32 v62, 0x90, v130
	v_pk_add_f32 v[58:59], v[58:59], 1.0 op_sel_hi:[1,0]
	s_nop 0
	v_div_scale_f32 v63, s[30:31], v58, v58, v52
	v_rcp_f32_e32 v65, v63
	v_rcp_f32_e32 v60, v59
	s_nop 0
	v_mul_f32_e32 v53, v53, v60
	v_mul_f32_e32 v61, 0xbfb8aa3b, v55
	v_fma_f32 v59, -v63, v65, 1.0
	v_fmac_f32_e32 v65, v59, v65
	v_mul_f32_e32 v60, 0xbfb8aa3b, v54
	v_exp_f32_e32 v60, v60
	v_exp_f32_e32 v61, v61
	v_rcp_f32_e32 v59, v58
	s_nop 0
	v_mul_f32_e32 v52, v52, v59
	v_pk_add_f32 v[60:61], v[60:61], 1.0 op_sel_hi:[1,0]
	v_pk_mul_f32 v[48:49], v[48:49], v[52:53]
	v_div_scale_f32 v63, s[30:31], v61, v61, v55
	v_rcp_f32_e32 v64, v63
	v_cvt_pk_bf16_f32 v52, v48, v49
	v_fma_f32 v48, -v63, v64, 1.0
	v_fmac_f32_e32 v64, v48, v64
	v_div_scale_f32 v53, s[30:31], v60, v60, v54
	v_rcp_f32_e32 v48, v61
	s_nop 0
	v_mul_f32_e32 v49, v55, v48
	v_rcp_f32_e32 v48, v60
	s_nop 0
	v_mul_f32_e32 v48, v54, v48
	v_pk_mul_f32 v[48:49], v[50:51], v[48:49]
	s_nop 0
	v_cvt_pk_bf16_f32 v53, v48, v49
	v_mad_i64_i32 v[48:49], s[30:31], v62, s53, v[120:121]
	v_lshl_add_u64 v[48:49], v[48:49], 0, v[122:123]
	flat_store_dwordx2 v[48:49], v[52:53]
	v_mul_f32_e32 v50, 0xbfb8aa3b, v44
	v_mul_f32_e32 v51, 0xbfb8aa3b, v45
	v_exp_f32_e32 v50, v50
	v_exp_f32_e32 v51, v51
	v_add_u32_e32 v54, 0xa0, v130
	v_pk_add_f32 v[50:51], v[50:51], 1.0 op_sel_hi:[1,0]
	s_nop 0
	v_div_scale_f32 v55, s[30:31], v50, v50, v44
	v_rcp_f32_e32 v59, v55
	v_rcp_f32_e32 v52, v51
	s_nop 0
	v_mul_f32_e32 v45, v45, v52
	v_mul_f32_e32 v53, 0xbfb8aa3b, v47
	v_fma_f32 v51, -v55, v59, 1.0
	v_fmac_f32_e32 v59, v51, v59
	v_mul_f32_e32 v52, 0xbfb8aa3b, v46
	v_exp_f32_e32 v52, v52
	v_exp_f32_e32 v53, v53
	v_rcp_f32_e32 v51, v50
	s_nop 0
	v_mul_f32_e32 v44, v44, v51
	v_pk_add_f32 v[52:53], v[52:53], 1.0 op_sel_hi:[1,0]
	v_pk_mul_f32 v[40:41], v[40:41], v[44:45]
	v_div_scale_f32 v55, s[30:31], v53, v53, v47
	v_rcp_f32_e32 v58, v55
	v_cvt_pk_bf16_f32 v44, v40, v41
	v_fma_f32 v40, -v55, v58, 1.0
	v_fmac_f32_e32 v58, v40, v58
	v_div_scale_f32 v45, s[30:31], v52, v52, v46
	v_rcp_f32_e32 v40, v53
	s_nop 0
	v_mul_f32_e32 v41, v47, v40
	v_rcp_f32_e32 v40, v52
	s_nop 0
	v_mul_f32_e32 v40, v46, v40
	v_pk_mul_f32 v[40:41], v[42:43], v[40:41]
	s_nop 0
	v_cvt_pk_bf16_f32 v45, v40, v41
	v_mad_i64_i32 v[40:41], s[30:31], v54, s53, v[120:121]
	v_lshl_add_u64 v[40:41], v[40:41], 0, v[122:123]
	flat_store_dwordx2 v[40:41], v[44:45]
	v_mul_f32_e32 v42, 0xbfb8aa3b, v36
	v_mul_f32_e32 v43, 0xbfb8aa3b, v37
	v_exp_f32_e32 v42, v42
	v_exp_f32_e32 v43, v43
	v_add_u32_e32 v46, 0xb0, v130
	v_pk_add_f32 v[42:43], v[42:43], 1.0 op_sel_hi:[1,0]
	s_nop 0
	v_div_scale_f32 v47, s[30:31], v42, v42, v36
	v_rcp_f32_e32 v51, v47
	v_rcp_f32_e32 v44, v43
	s_nop 0
	v_mul_f32_e32 v37, v37, v44
	v_mul_f32_e32 v45, 0xbfb8aa3b, v39
	v_fma_f32 v43, -v47, v51, 1.0
	v_fmac_f32_e32 v51, v43, v51
	v_mul_f32_e32 v44, 0xbfb8aa3b, v38
	v_exp_f32_e32 v44, v44
	v_exp_f32_e32 v45, v45
	v_rcp_f32_e32 v43, v42
	s_nop 0
	v_mul_f32_e32 v36, v36, v43
	v_pk_add_f32 v[44:45], v[44:45], 1.0 op_sel_hi:[1,0]
	v_pk_mul_f32 v[32:33], v[32:33], v[36:37]
	v_div_scale_f32 v47, s[30:31], v45, v45, v39
	v_rcp_f32_e32 v50, v47
	v_cvt_pk_bf16_f32 v36, v32, v33
	v_fma_f32 v32, -v47, v50, 1.0
	v_fmac_f32_e32 v50, v32, v50
	v_div_scale_f32 v37, s[30:31], v44, v44, v38
	v_rcp_f32_e32 v42, v37
	v_rcp_f32_e32 v32, v45
	s_nop 0
	v_mul_f32_e32 v33, v39, v32
	v_fma_f32 v32, -v37, v42, 1.0
	v_fmac_f32_e32 v42, v32, v42
	v_div_scale_f32 v32, vcc, v38, v44, v38
	v_mul_f32_e32 v39, v32, v42
	v_fma_f32 v43, -v37, v39, v32
	v_rcp_f32_e32 v32, v44
	s_nop 0
	v_mul_f32_e32 v32, v38, v32
	v_pk_mul_f32 v[32:33], v[34:35], v[32:33]
	s_nop 0
	v_cvt_pk_bf16_f32 v37, v32, v33
	v_mad_i64_i32 v[32:33], s[30:31], v46, s53, v[120:121]
	v_lshl_add_u64 v[32:33], v[32:33], 0, v[122:123]
	flat_store_dwordx2 v[32:33], v[36:37]
	v_mul_f32_e32 v34, 0xbfb8aa3b, v28
	v_mul_f32_e32 v35, 0xbfb8aa3b, v29
	v_exp_f32_e32 v34, v34
	v_exp_f32_e32 v35, v35
	s_nop 0
	v_pk_add_f32 v[34:35], v[34:35], 1.0 op_sel_hi:[1,0]
	s_nop 0
	v_div_scale_f32 v38, s[30:31], v34, v34, v28
	v_rcp_f32_e32 v42, v38
	v_rcp_f32_e32 v36, v35
	s_nop 0
	v_mul_f32_e32 v29, v29, v36
	v_mul_f32_e32 v37, 0xbfb8aa3b, v31
	v_fma_f32 v35, -v38, v42, 1.0
	v_fmac_f32_e32 v42, v35, v42
	v_mul_f32_e32 v36, 0xbfb8aa3b, v30
	v_exp_f32_e32 v36, v36
	v_exp_f32_e32 v37, v37
	v_rcp_f32_e32 v35, v34
	s_nop 0
	v_mul_f32_e32 v28, v28, v35
	v_pk_add_f32 v[36:37], v[36:37], 1.0 op_sel_hi:[1,0]
	v_pk_mul_f32 v[24:25], v[24:25], v[28:29]
	v_div_scale_f32 v38, s[30:31], v37, v37, v31
	v_rcp_f32_e32 v39, v38
	v_cvt_pk_bf16_f32 v24, v24, v25
	v_div_scale_f32 v34, s[30:31], v36, v36, v30
	v_fma_f32 v25, -v38, v39, 1.0
	v_fmac_f32_e32 v39, v25, v39
	v_rcp_f32_e32 v35, v34
	v_rcp_f32_e32 v25, v37
	s_nop 0
	v_mul_f32_e32 v29, v31, v25
	v_fma_f32 v25, -v34, v35, 1.0
	v_fmac_f32_e32 v35, v25, v35
	v_div_scale_f32 v25, vcc, v30, v36, v30
	v_mul_f32_e32 v28, v25, v35
	v_fma_f32 v31, -v34, v28, v25
	v_rcp_f32_e32 v25, v36
	s_nop 0
	v_mul_f32_e32 v28, v30, v25
	v_pk_mul_f32 v[26:27], v[26:27], v[28:29]
	s_nop 0
	v_cvt_pk_bf16_f32 v25, v26, v27
	flat_store_dwordx2 v[56:57], v[24:25] offset:128
	v_mul_f32_e32 v24, 0xbfb8aa3b, v20
	v_mul_f32_e32 v25, 0xbfb8aa3b, v21
	v_exp_f32_e32 v24, v24
	v_exp_f32_e32 v25, v25
	s_nop 0
	v_pk_add_f32 v[24:25], v[24:25], 1.0 op_sel_hi:[1,0]
	s_nop 0
	v_div_scale_f32 v28, s[30:31], v24, v24, v20
	v_rcp_f32_e32 v30, v28
	v_rcp_f32_e32 v26, v25
	s_nop 0
	v_mul_f32_e32 v21, v21, v26
	v_mul_f32_e32 v27, 0xbfb8aa3b, v23
	v_fma_f32 v25, -v28, v30, 1.0
	v_fmac_f32_e32 v30, v25, v30
	v_mul_f32_e32 v26, 0xbfb8aa3b, v22
	v_exp_f32_e32 v26, v26
	v_exp_f32_e32 v27, v27
	v_rcp_f32_e32 v25, v24
	s_nop 0
	v_mul_f32_e32 v20, v20, v25
	v_pk_add_f32 v[26:27], v[26:27], 1.0 op_sel_hi:[1,0]
	v_pk_mul_f32 v[16:17], v[16:17], v[20:21]
	v_div_scale_f32 v28, s[30:31], v27, v27, v23
	v_rcp_f32_e32 v29, v28
	v_cvt_pk_bf16_f32 v16, v16, v17
	v_div_scale_f32 v24, s[30:31], v26, v26, v22
	v_fma_f32 v17, -v28, v29, 1.0
	v_fmac_f32_e32 v29, v17, v29
	v_rcp_f32_e32 v25, v24
	v_rcp_f32_e32 v17, v27
	s_nop 0
	v_mul_f32_e32 v21, v23, v17
	v_fma_f32 v17, -v24, v25, 1.0
	v_fmac_f32_e32 v25, v17, v25
	v_div_scale_f32 v17, vcc, v22, v26, v22
	v_mul_f32_e32 v20, v17, v25
	v_fma_f32 v23, -v24, v20, v17
	v_rcp_f32_e32 v17, v26
	s_nop 0
	v_mul_f32_e32 v20, v22, v17
	v_pk_mul_f32 v[18:19], v[18:19], v[20:21]
	s_nop 0
	v_cvt_pk_bf16_f32 v17, v18, v19
	flat_store_dwordx2 v[48:49], v[16:17] offset:128
	v_mul_f32_e32 v16, 0xbfb8aa3b, v12
	v_mul_f32_e32 v17, 0xbfb8aa3b, v13
	v_exp_f32_e32 v16, v16
	v_exp_f32_e32 v17, v17
	s_nop 0
	v_pk_add_f32 v[16:17], v[16:17], 1.0 op_sel_hi:[1,0]
	s_nop 0
	v_div_scale_f32 v20, s[30:31], v16, v16, v12
	v_rcp_f32_e32 v22, v20
	v_rcp_f32_e32 v18, v17
	s_nop 0
	v_mul_f32_e32 v13, v13, v18
	v_mul_f32_e32 v19, 0xbfb8aa3b, v15
	v_fma_f32 v17, -v20, v22, 1.0
	v_fmac_f32_e32 v22, v17, v22
	v_mul_f32_e32 v18, 0xbfb8aa3b, v14
	v_exp_f32_e32 v18, v18
	v_exp_f32_e32 v19, v19
	v_rcp_f32_e32 v17, v16
	s_nop 0
	v_mul_f32_e32 v12, v12, v17
	v_pk_add_f32 v[18:19], v[18:19], 1.0 op_sel_hi:[1,0]
	v_pk_mul_f32 v[8:9], v[8:9], v[12:13]
	v_div_scale_f32 v20, s[30:31], v19, v19, v15
	v_rcp_f32_e32 v21, v20
	v_cvt_pk_bf16_f32 v8, v8, v9
	v_div_scale_f32 v16, s[30:31], v18, v18, v14
	v_fma_f32 v9, -v20, v21, 1.0
	v_fmac_f32_e32 v21, v9, v21
	v_rcp_f32_e32 v17, v16
	v_rcp_f32_e32 v9, v19
	s_nop 0
	v_mul_f32_e32 v13, v15, v9
	v_fma_f32 v9, -v16, v17, 1.0
	v_fmac_f32_e32 v17, v9, v17
	v_div_scale_f32 v9, vcc, v14, v18, v14
	v_mul_f32_e32 v12, v9, v17
	v_fma_f32 v15, -v16, v12, v9
	v_rcp_f32_e32 v9, v18
	s_nop 0
	v_mul_f32_e32 v12, v14, v9
	v_pk_mul_f32 v[10:11], v[10:11], v[12:13]
	s_nop 0
	v_cvt_pk_bf16_f32 v9, v10, v11
	flat_store_dwordx2 v[40:41], v[8:9] offset:128
	v_mul_f32_e32 v8, 0xbfb8aa3b, v4
	v_mul_f32_e32 v9, 0xbfb8aa3b, v5
	v_exp_f32_e32 v8, v8
	v_exp_f32_e32 v9, v9
	s_nop 0
	v_pk_add_f32 v[8:9], v[8:9], 1.0 op_sel_hi:[1,0]
	s_nop 0
	v_div_scale_f32 v12, s[30:31], v8, v8, v4
	v_rcp_f32_e32 v14, v12
	v_rcp_f32_e32 v10, v9
	s_nop 0
	v_mul_f32_e32 v5, v5, v10
	v_mul_f32_e32 v11, 0xbfb8aa3b, v7
	v_fma_f32 v9, -v12, v14, 1.0
	v_fmac_f32_e32 v14, v9, v14
	v_mul_f32_e32 v10, 0xbfb8aa3b, v6
	v_exp_f32_e32 v10, v10
	v_exp_f32_e32 v11, v11
	v_rcp_f32_e32 v9, v8
	s_nop 0
	v_mul_f32_e32 v4, v4, v9
	v_pk_add_f32 v[10:11], v[10:11], 1.0 op_sel_hi:[1,0]
	v_pk_mul_f32 v[0:1], v[0:1], v[4:5]
	v_div_scale_f32 v12, s[30:31], v11, v11, v7
	v_rcp_f32_e32 v13, v12
	v_cvt_pk_bf16_f32 v0, v0, v1
	v_div_scale_f32 v8, s[30:31], v10, v10, v6
	v_fma_f32 v1, -v12, v13, 1.0
	v_fmac_f32_e32 v13, v1, v13
	v_rcp_f32_e32 v9, v8
	v_rcp_f32_e32 v1, v11
	s_nop 0
	v_mul_f32_e32 v5, v7, v1
	v_fma_f32 v1, -v8, v9, 1.0
	v_fmac_f32_e32 v9, v1, v9
	v_div_scale_f32 v1, vcc, v6, v10, v6
	v_mul_f32_e32 v4, v1, v9
	v_fma_f32 v7, -v8, v4, v1
	v_rcp_f32_e32 v1, v10
	s_nop 0
	v_mul_f32_e32 v4, v6, v1
	v_pk_mul_f32 v[2:3], v[2:3], v[4:5]
	s_nop 0
	v_cvt_pk_bf16_f32 v1, v2, v3
	flat_store_dwordx2 v[32:33], v[0:1] offset:128
	s_andn2_b64 vcc, exec, s[0:1]
	s_mov_b32 s56, s54
	s_mov_b32 s38, s55
	s_cbranch_vccz .LBB0_695

.LBB0_1800:
	s_or_b64 exec, exec, s[38:39]
	v_mul_f32_e32 v131, 0xbfb8aa3b, v124
	v_exp_f32_e32 v132, v131
	v_mul_f32_e32 v131, 0xbfb8aa3b, v125
	v_exp_f32_e32 v133, v131
	v_or_b32_e32 v130, s30, v152
	s_lshl_b32 s38, s56, 7
	v_lshlrev_b32_e32 v131, 4, v145
	v_pk_add_f32 v[132:133], v[132:133], 1.0 op_sel_hi:[1,0]
	v_lshlrev_b32_e32 v134, 2, v144
	v_or3_b32 v134, v131, s38, v134
	v_add_u32_e32 v130, v130, v153
	v_ashrrev_i32_e32 v135, 31, v134
	v_div_scale_f32 v139, s[30:31], v132, v132, v124
	v_rcp_f32_e32 v140, v139
	v_rcp_f32_e32 v131, v133
	s_nop 0
	v_mul_f32_e32 v125, v125, v131
	v_fma_f32 v131, -v139, v140, 1.0
	v_fmac_f32_e32 v140, v131, v140
	v_mul_f32_e32 v136, 0xbfb8aa3b, v126
	v_mul_f32_e32 v137, 0xbfb8aa3b, v127
	v_exp_f32_e32 v136, v136
	v_exp_f32_e32 v137, v137
	v_rcp_f32_e32 v131, v132
	s_nop 0
	v_mul_f32_e32 v124, v124, v131
	v_pk_add_f32 v[136:137], v[136:137], 1.0 op_sel_hi:[1,0]
	v_pk_mul_f32 v[120:121], v[120:121], v[124:125]
	v_div_scale_f32 v133, s[30:31], v137, v137, v127
	v_rcp_f32_e32 v138, v133
	v_cvt_pk_bf16_f32 v132, v120, v121
	v_fma_f32 v120, -v133, v138, 1.0
	v_fmac_f32_e32 v138, v120, v138
	v_div_scale_f32 v124, s[30:31], v136, v136, v126
	v_rcp_f32_e32 v120, v137
	s_nop 0
	v_mul_f32_e32 v121, v127, v120
	v_rcp_f32_e32 v120, v136
	s_nop 0
	v_mul_f32_e32 v120, v126, v120
	v_pk_mul_f32 v[120:121], v[122:123], v[120:121]
	v_lshlrev_b64 v[122:123], 1, v[134:135]
	v_cvt_pk_bf16_f32 v133, v120, v121
	v_mov_b64_e32 v[120:121], s[6:7]
	v_mad_i64_i32 v[124:125], s[30:31], v130, s53, v[120:121]
	v_lshl_add_u64 v[124:125], v[124:125], 0, v[122:123]
	flat_store_dwordx2 v[124:125], v[132:133]
	v_mul_f32_e32 v126, 0xbfb8aa3b, v116
	v_mul_f32_e32 v127, 0xbfb8aa3b, v117
	v_exp_f32_e32 v126, v126
	v_exp_f32_e32 v127, v127
	v_or_b32_e32 v134, 16, v130
	v_pk_add_f32 v[126:127], v[126:127], 1.0 op_sel_hi:[1,0]
	s_nop 0
	v_div_scale_f32 v136, s[30:31], v126, v126, v116
	v_rcp_f32_e32 v137, v136
	v_rcp_f32_e32 v131, v127
	s_nop 0
	v_mul_f32_e32 v117, v117, v131
	v_fma_f32 v127, -v136, v137, 1.0
	v_fmac_f32_e32 v137, v127, v137
	v_mul_f32_e32 v132, 0xbfb8aa3b, v118
	v_mul_f32_e32 v133, 0xbfb8aa3b, v119
	v_exp_f32_e32 v132, v132
	v_exp_f32_e32 v133, v133
	v_rcp_f32_e32 v127, v126
	s_nop 0
	v_mul_f32_e32 v116, v116, v127
	v_pk_add_f32 v[132:133], v[132:133], 1.0 op_sel_hi:[1,0]
	v_pk_mul_f32 v[112:113], v[112:113], v[116:117]
	v_div_scale_f32 v131, s[30:31], v133, v133, v119
	v_rcp_f32_e32 v135, v131
	v_cvt_pk_bf16_f32 v116, v112, v113
	v_fma_f32 v112, -v131, v135, 1.0
	v_fmac_f32_e32 v135, v112, v135
	v_div_scale_f32 v117, s[30:31], v132, v132, v118
	v_rcp_f32_e32 v112, v133
	s_nop 0
	v_mul_f32_e32 v113, v119, v112
	v_rcp_f32_e32 v112, v132
	s_nop 0
	v_mul_f32_e32 v112, v118, v112
	v_pk_mul_f32 v[112:113], v[114:115], v[112:113]
	s_nop 0
	v_cvt_pk_bf16_f32 v117, v112, v113
	v_mad_i64_i32 v[112:113], s[30:31], v134, s53, v[120:121]
	v_lshl_add_u64 v[112:113], v[112:113], 0, v[122:123]
	flat_store_dwordx2 v[112:113], v[116:117]
	v_mul_f32_e32 v114, 0xbfb8aa3b, v108
	v_mul_f32_e32 v115, 0xbfb8aa3b, v109
	v_exp_f32_e32 v114, v114
	v_exp_f32_e32 v115, v115
	v_or_b32_e32 v118, 32, v130
	v_pk_add_f32 v[114:115], v[114:115], 1.0 op_sel_hi:[1,0]
	s_nop 0
	v_div_scale_f32 v119, s[30:31], v114, v114, v108
	v_rcp_f32_e32 v127, v119
	v_rcp_f32_e32 v116, v115
	s_nop 0
	v_mul_f32_e32 v109, v109, v116
	v_mul_f32_e32 v117, 0xbfb8aa3b, v111
	v_fma_f32 v115, -v119, v127, 1.0
	v_fmac_f32_e32 v127, v115, v127
	v_mul_f32_e32 v116, 0xbfb8aa3b, v110
	v_exp_f32_e32 v116, v116
	v_exp_f32_e32 v117, v117
	v_rcp_f32_e32 v115, v114
	s_nop 0
	v_mul_f32_e32 v108, v108, v115
	v_pk_add_f32 v[116:117], v[116:117], 1.0 op_sel_hi:[1,0]
	v_pk_mul_f32 v[104:105], v[104:105], v[108:109]
	v_div_scale_f32 v119, s[30:31], v117, v117, v111
	v_rcp_f32_e32 v126, v119
	v_cvt_pk_bf16_f32 v108, v104, v105
	v_fma_f32 v104, -v119, v126, 1.0
	v_fmac_f32_e32 v126, v104, v126
	v_div_scale_f32 v109, s[30:31], v116, v116, v110
	v_rcp_f32_e32 v104, v117
	s_nop 0
	v_mul_f32_e32 v105, v111, v104
	v_rcp_f32_e32 v104, v116
	s_nop 0
	v_mul_f32_e32 v104, v110, v104
	v_pk_mul_f32 v[104:105], v[106:107], v[104:105]
	s_nop 0
	v_cvt_pk_bf16_f32 v109, v104, v105
	v_mad_i64_i32 v[104:105], s[30:31], v118, s53, v[120:121]
	v_lshl_add_u64 v[104:105], v[104:105], 0, v[122:123]
	flat_store_dwordx2 v[104:105], v[108:109]
	v_mul_f32_e32 v106, 0xbfb8aa3b, v100
	v_mul_f32_e32 v107, 0xbfb8aa3b, v101
	v_exp_f32_e32 v106, v106
	v_exp_f32_e32 v107, v107
	v_or_b32_e32 v110, 48, v130
	v_pk_add_f32 v[106:107], v[106:107], 1.0 op_sel_hi:[1,0]
	s_nop 0
	v_div_scale_f32 v111, s[30:31], v106, v106, v100
	v_rcp_f32_e32 v115, v111
	v_rcp_f32_e32 v108, v107
	s_nop 0
	v_mul_f32_e32 v101, v101, v108
	v_mul_f32_e32 v109, 0xbfb8aa3b, v103
	v_fma_f32 v107, -v111, v115, 1.0
	v_fmac_f32_e32 v115, v107, v115
	v_mul_f32_e32 v108, 0xbfb8aa3b, v102
	v_exp_f32_e32 v108, v108
	v_exp_f32_e32 v109, v109
	v_rcp_f32_e32 v107, v106
	s_nop 0
	v_mul_f32_e32 v100, v100, v107
	v_pk_add_f32 v[108:109], v[108:109], 1.0 op_sel_hi:[1,0]
	v_pk_mul_f32 v[96:97], v[96:97], v[100:101]
	v_div_scale_f32 v111, s[30:31], v109, v109, v103
	v_rcp_f32_e32 v114, v111
	v_cvt_pk_bf16_f32 v100, v96, v97
	v_fma_f32 v96, -v111, v114, 1.0
	v_fmac_f32_e32 v114, v96, v114
	v_div_scale_f32 v101, s[30:31], v108, v108, v102
	v_rcp_f32_e32 v106, v101
	v_rcp_f32_e32 v96, v109
	s_nop 0
	v_mul_f32_e32 v97, v103, v96
	v_fma_f32 v96, -v101, v106, 1.0
	v_fmac_f32_e32 v106, v96, v106
	v_div_scale_f32 v96, vcc, v102, v108, v102
	v_mul_f32_e32 v103, v96, v106
	v_fma_f32 v107, -v101, v103, v96
	v_rcp_f32_e32 v96, v108
	s_nop 0
	v_mul_f32_e32 v96, v102, v96
	v_pk_mul_f32 v[96:97], v[98:99], v[96:97]
	s_nop 0
	v_cvt_pk_bf16_f32 v101, v96, v97
	v_mad_i64_i32 v[96:97], s[30:31], v110, s53, v[120:121]
	v_lshl_add_u64 v[96:97], v[96:97], 0, v[122:123]
	flat_store_dwordx2 v[96:97], v[100:101]
	v_mul_f32_e32 v98, 0xbfb8aa3b, v92
	v_mul_f32_e32 v99, 0xbfb8aa3b, v93
	v_exp_f32_e32 v98, v98
	v_exp_f32_e32 v99, v99
	s_nop 0
	v_pk_add_f32 v[98:99], v[98:99], 1.0 op_sel_hi:[1,0]
	s_nop 0
	v_div_scale_f32 v102, s[30:31], v98, v98, v92
	v_rcp_f32_e32 v106, v102
	v_rcp_f32_e32 v100, v99
	s_nop 0
	v_mul_f32_e32 v93, v93, v100
	v_mul_f32_e32 v101, 0xbfb8aa3b, v95
	v_fma_f32 v99, -v102, v106, 1.0
	v_fmac_f32_e32 v106, v99, v106
	v_mul_f32_e32 v100, 0xbfb8aa3b, v94
	v_exp_f32_e32 v100, v100
	v_exp_f32_e32 v101, v101
	v_rcp_f32_e32 v99, v98
	s_nop 0
	v_mul_f32_e32 v92, v92, v99
	v_pk_add_f32 v[100:101], v[100:101], 1.0 op_sel_hi:[1,0]
	v_pk_mul_f32 v[88:89], v[88:89], v[92:93]
	v_div_scale_f32 v102, s[30:31], v101, v101, v95
	v_rcp_f32_e32 v103, v102
	v_cvt_pk_bf16_f32 v88, v88, v89
	v_div_scale_f32 v98, s[30:31], v100, v100, v94
	v_fma_f32 v89, -v102, v103, 1.0
	v_fmac_f32_e32 v103, v89, v103
	v_rcp_f32_e32 v99, v98
	v_rcp_f32_e32 v89, v101
	s_nop 0
	v_mul_f32_e32 v93, v95, v89
	v_fma_f32 v89, -v98, v99, 1.0
	v_fmac_f32_e32 v99, v89, v99
	v_div_scale_f32 v89, vcc, v94, v100, v94
	v_mul_f32_e32 v92, v89, v99
	v_fma_f32 v95, -v98, v92, v89
	v_rcp_f32_e32 v89, v100
	s_nop 0
	v_mul_f32_e32 v92, v94, v89
	v_pk_mul_f32 v[90:91], v[90:91], v[92:93]
	s_nop 0
	v_cvt_pk_bf16_f32 v89, v90, v91
	flat_store_dwordx2 v[124:125], v[88:89] offset:128
	v_mul_f32_e32 v88, 0xbfb8aa3b, v84
	v_mul_f32_e32 v89, 0xbfb8aa3b, v85
	v_exp_f32_e32 v88, v88
	v_exp_f32_e32 v89, v89
	s_nop 0
	v_pk_add_f32 v[88:89], v[88:89], 1.0 op_sel_hi:[1,0]
	s_nop 0
	v_div_scale_f32 v92, s[30:31], v88, v88, v84
	v_rcp_f32_e32 v94, v92
	v_rcp_f32_e32 v90, v89
	s_nop 0
	v_mul_f32_e32 v85, v85, v90
	v_mul_f32_e32 v91, 0xbfb8aa3b, v87
	v_fma_f32 v89, -v92, v94, 1.0
	v_fmac_f32_e32 v94, v89, v94
	v_mul_f32_e32 v90, 0xbfb8aa3b, v86
	v_exp_f32_e32 v90, v90
	v_exp_f32_e32 v91, v91
	v_rcp_f32_e32 v89, v88
	s_nop 0
	v_mul_f32_e32 v84, v84, v89
	v_pk_add_f32 v[90:91], v[90:91], 1.0 op_sel_hi:[1,0]
	v_pk_mul_f32 v[80:81], v[80:81], v[84:85]
	v_div_scale_f32 v92, s[30:31], v91, v91, v87
	v_rcp_f32_e32 v93, v92
	v_cvt_pk_bf16_f32 v80, v80, v81
	v_div_scale_f32 v88, s[30:31], v90, v90, v86
	v_fma_f32 v81, -v92, v93, 1.0
	v_fmac_f32_e32 v93, v81, v93
	v_rcp_f32_e32 v89, v88
	v_rcp_f32_e32 v81, v91
	s_nop 0
	v_mul_f32_e32 v85, v87, v81
	v_fma_f32 v81, -v88, v89, 1.0
	v_fmac_f32_e32 v89, v81, v89
	v_div_scale_f32 v81, vcc, v86, v90, v86
	v_mul_f32_e32 v84, v81, v89
	v_fma_f32 v87, -v88, v84, v81
	v_rcp_f32_e32 v81, v90
	s_nop 0
	v_mul_f32_e32 v84, v86, v81
	v_pk_mul_f32 v[82:83], v[82:83], v[84:85]
	s_nop 0
	v_cvt_pk_bf16_f32 v81, v82, v83
	flat_store_dwordx2 v[112:113], v[80:81] offset:128
	v_mul_f32_e32 v80, 0xbfb8aa3b, v76
	v_mul_f32_e32 v81, 0xbfb8aa3b, v77
	v_exp_f32_e32 v80, v80
	v_exp_f32_e32 v81, v81
	s_nop 0
	v_pk_add_f32 v[80:81], v[80:81], 1.0 op_sel_hi:[1,0]
	s_nop 0
	v_div_scale_f32 v84, s[30:31], v80, v80, v76
	v_rcp_f32_e32 v86, v84
	v_rcp_f32_e32 v82, v81
	s_nop 0
	v_mul_f32_e32 v77, v77, v82
	v_mul_f32_e32 v83, 0xbfb8aa3b, v79
	v_fma_f32 v81, -v84, v86, 1.0
	v_fmac_f32_e32 v86, v81, v86
	v_mul_f32_e32 v82, 0xbfb8aa3b, v78
	v_exp_f32_e32 v82, v82
	v_exp_f32_e32 v83, v83
	v_rcp_f32_e32 v81, v80
	s_nop 0
	v_mul_f32_e32 v76, v76, v81
	v_pk_add_f32 v[82:83], v[82:83], 1.0 op_sel_hi:[1,0]
	v_pk_mul_f32 v[72:73], v[72:73], v[76:77]
	v_div_scale_f32 v84, s[30:31], v83, v83, v79
	v_rcp_f32_e32 v85, v84
	v_cvt_pk_bf16_f32 v72, v72, v73
	v_div_scale_f32 v80, s[30:31], v82, v82, v78
	v_fma_f32 v73, -v84, v85, 1.0
	v_fmac_f32_e32 v85, v73, v85
	v_rcp_f32_e32 v81, v80
	v_rcp_f32_e32 v73, v83
	s_nop 0
	v_mul_f32_e32 v77, v79, v73
	v_fma_f32 v73, -v80, v81, 1.0
	v_fmac_f32_e32 v81, v73, v81
	v_div_scale_f32 v73, vcc, v78, v82, v78
	v_mul_f32_e32 v76, v73, v81
	v_fma_f32 v79, -v80, v76, v73
	v_rcp_f32_e32 v73, v82
	s_nop 0
	v_mul_f32_e32 v76, v78, v73
	v_pk_mul_f32 v[74:75], v[74:75], v[76:77]
	s_nop 0
	v_cvt_pk_bf16_f32 v73, v74, v75
	flat_store_dwordx2 v[104:105], v[72:73] offset:128
	v_mul_f32_e32 v72, 0xbfb8aa3b, v68
	v_mul_f32_e32 v73, 0xbfb8aa3b, v69
	v_exp_f32_e32 v72, v72
	v_exp_f32_e32 v73, v73
	s_nop 0
	v_pk_add_f32 v[72:73], v[72:73], 1.0 op_sel_hi:[1,0]
	s_nop 0
	v_div_scale_f32 v76, s[30:31], v72, v72, v68
	v_rcp_f32_e32 v78, v76
	v_rcp_f32_e32 v74, v73
	s_nop 0
	v_mul_f32_e32 v69, v69, v74
	v_mul_f32_e32 v75, 0xbfb8aa3b, v71
	v_fma_f32 v73, -v76, v78, 1.0
	v_fmac_f32_e32 v78, v73, v78
	v_mul_f32_e32 v74, 0xbfb8aa3b, v70
	v_exp_f32_e32 v74, v74
	v_exp_f32_e32 v75, v75
	v_rcp_f32_e32 v73, v72
	s_nop 0
	v_mul_f32_e32 v68, v68, v73
	v_pk_add_f32 v[74:75], v[74:75], 1.0 op_sel_hi:[1,0]
	v_pk_mul_f32 v[64:65], v[64:65], v[68:69]
	v_div_scale_f32 v76, s[30:31], v75, v75, v71
	v_rcp_f32_e32 v77, v76
	v_cvt_pk_bf16_f32 v64, v64, v65
	v_div_scale_f32 v72, s[30:31], v74, v74, v70
	v_fma_f32 v65, -v76, v77, 1.0
	v_fmac_f32_e32 v77, v65, v77
	v_rcp_f32_e32 v73, v72
	v_rcp_f32_e32 v65, v75
	s_nop 0
	v_mul_f32_e32 v69, v71, v65
	v_fma_f32 v65, -v72, v73, 1.0
	v_fmac_f32_e32 v73, v65, v73
	v_rcp_f32_e32 v65, v74
	s_nop 0
	v_mul_f32_e32 v68, v70, v65
	v_pk_mul_f32 v[66:67], v[66:67], v[68:69]
	s_nop 0
	v_cvt_pk_bf16_f32 v65, v66, v67
	flat_store_dwordx2 v[96:97], v[64:65] offset:128
	v_mul_f32_e32 v64, 0xbfb8aa3b, v60
	v_mul_f32_e32 v65, 0xbfb8aa3b, v61
	v_exp_f32_e32 v64, v64
	v_exp_f32_e32 v65, v65
	v_add_u32_e32 v68, 0x80, v130
	v_pk_add_f32 v[64:65], v[64:65], 1.0 op_sel_hi:[1,0]
	s_nop 0
	v_div_scale_f32 v69, s[30:31], v64, v64, v60
	v_rcp_f32_e32 v71, v69
	v_rcp_f32_e32 v66, v65
	s_nop 0
	v_mul_f32_e32 v61, v61, v66
	v_mul_f32_e32 v67, 0xbfb8aa3b, v63
	v_fma_f32 v65, -v69, v71, 1.0
	v_fmac_f32_e32 v71, v65, v71
	v_mul_f32_e32 v66, 0xbfb8aa3b, v62
	v_exp_f32_e32 v66, v66
	v_exp_f32_e32 v67, v67
	v_rcp_f32_e32 v65, v64
	s_nop 0
	v_mul_f32_e32 v60, v60, v65
	v_pk_add_f32 v[66:67], v[66:67], 1.0 op_sel_hi:[1,0]
	v_pk_mul_f32 v[56:57], v[56:57], v[60:61]
	v_div_scale_f32 v69, s[30:31], v67, v67, v63
	v_rcp_f32_e32 v70, v69
	v_cvt_pk_bf16_f32 v60, v56, v57
	v_fma_f32 v56, -v69, v70, 1.0
	v_fmac_f32_e32 v70, v56, v70
	v_div_scale_f32 v61, s[30:31], v66, v66, v62
	v_rcp_f32_e32 v56, v67
	s_nop 0
	v_mul_f32_e32 v57, v63, v56
	v_rcp_f32_e32 v56, v66
	s_nop 0
	v_mul_f32_e32 v56, v62, v56
	v_pk_mul_f32 v[56:57], v[58:59], v[56:57]
	s_nop 0
	v_cvt_pk_bf16_f32 v61, v56, v57
	v_mad_i64_i32 v[56:57], s[30:31], v68, s53, v[120:121]
	v_lshl_add_u64 v[56:57], v[56:57], 0, v[122:123]
	flat_store_dwordx2 v[56:57], v[60:61]
	v_mul_f32_e32 v58, 0xbfb8aa3b, v52
	v_mul_f32_e32 v59, 0xbfb8aa3b, v53
	v_exp_f32_e32 v58, v58
	v_exp_f32_e32 v59, v59
	v_add_u32_e32 v62, 0x90, v130
	v_pk_add_f32 v[58:59], v[58:59], 1.0 op_sel_hi:[1,0]
	s_nop 0
	v_div_scale_f32 v63, s[30:31], v58, v58, v52
	v_rcp_f32_e32 v65, v63
	v_rcp_f32_e32 v60, v59
	s_nop 0
	v_mul_f32_e32 v53, v53, v60
	v_mul_f32_e32 v61, 0xbfb8aa3b, v55
	v_fma_f32 v59, -v63, v65, 1.0
	v_fmac_f32_e32 v65, v59, v65
	v_mul_f32_e32 v60, 0xbfb8aa3b, v54
	v_exp_f32_e32 v60, v60
	v_exp_f32_e32 v61, v61
	v_rcp_f32_e32 v59, v58
	s_nop 0
	v_mul_f32_e32 v52, v52, v59
	v_pk_add_f32 v[60:61], v[60:61], 1.0 op_sel_hi:[1,0]
	v_pk_mul_f32 v[48:49], v[48:49], v[52:53]
	v_div_scale_f32 v63, s[30:31], v61, v61, v55
	v_rcp_f32_e32 v64, v63
	v_cvt_pk_bf16_f32 v52, v48, v49
	v_fma_f32 v48, -v63, v64, 1.0
	v_fmac_f32_e32 v64, v48, v64
	v_div_scale_f32 v53, s[30:31], v60, v60, v54
	v_rcp_f32_e32 v48, v61
	s_nop 0
	v_mul_f32_e32 v49, v55, v48
	v_rcp_f32_e32 v48, v60
	s_nop 0
	v_mul_f32_e32 v48, v54, v48
	v_pk_mul_f32 v[48:49], v[50:51], v[48:49]
	s_nop 0
	v_cvt_pk_bf16_f32 v53, v48, v49
	v_mad_i64_i32 v[48:49], s[30:31], v62, s53, v[120:121]
	v_lshl_add_u64 v[48:49], v[48:49], 0, v[122:123]
	flat_store_dwordx2 v[48:49], v[52:53]
	v_mul_f32_e32 v50, 0xbfb8aa3b, v44
	v_mul_f32_e32 v51, 0xbfb8aa3b, v45
	v_exp_f32_e32 v50, v50
	v_exp_f32_e32 v51, v51
	v_add_u32_e32 v54, 0xa0, v130
	v_pk_add_f32 v[50:51], v[50:51], 1.0 op_sel_hi:[1,0]
	s_nop 0
	v_div_scale_f32 v55, s[30:31], v50, v50, v44
	v_rcp_f32_e32 v59, v55
	v_rcp_f32_e32 v52, v51
	s_nop 0
	v_mul_f32_e32 v45, v45, v52
	v_mul_f32_e32 v53, 0xbfb8aa3b, v47
	v_fma_f32 v51, -v55, v59, 1.0
	v_fmac_f32_e32 v59, v51, v59
	v_mul_f32_e32 v52, 0xbfb8aa3b, v46
	v_exp_f32_e32 v52, v52
	v_exp_f32_e32 v53, v53
	v_rcp_f32_e32 v51, v50
	s_nop 0
	v_mul_f32_e32 v44, v44, v51
	v_pk_add_f32 v[52:53], v[52:53], 1.0 op_sel_hi:[1,0]
	v_pk_mul_f32 v[40:41], v[40:41], v[44:45]
	v_div_scale_f32 v55, s[30:31], v53, v53, v47
	v_rcp_f32_e32 v58, v55
	v_cvt_pk_bf16_f32 v44, v40, v41
	v_fma_f32 v40, -v55, v58, 1.0
	v_fmac_f32_e32 v58, v40, v58
	v_div_scale_f32 v45, s[30:31], v52, v52, v46
	v_rcp_f32_e32 v40, v53
	s_nop 0
	v_mul_f32_e32 v41, v47, v40
	v_rcp_f32_e32 v40, v52
	s_nop 0
	v_mul_f32_e32 v40, v46, v40
	v_pk_mul_f32 v[40:41], v[42:43], v[40:41]
	s_nop 0
	v_cvt_pk_bf16_f32 v45, v40, v41
	v_mad_i64_i32 v[40:41], s[30:31], v54, s53, v[120:121]
	v_lshl_add_u64 v[40:41], v[40:41], 0, v[122:123]
	flat_store_dwordx2 v[40:41], v[44:45]
	v_mul_f32_e32 v42, 0xbfb8aa3b, v36
	v_mul_f32_e32 v43, 0xbfb8aa3b, v37
	v_exp_f32_e32 v42, v42
	v_exp_f32_e32 v43, v43
	v_add_u32_e32 v46, 0xb0, v130
	v_pk_add_f32 v[42:43], v[42:43], 1.0 op_sel_hi:[1,0]
	s_nop 0
	v_div_scale_f32 v47, s[30:31], v42, v42, v36
	v_rcp_f32_e32 v51, v47
	v_rcp_f32_e32 v44, v43
	s_nop 0
	v_mul_f32_e32 v37, v37, v44
	v_mul_f32_e32 v45, 0xbfb8aa3b, v39
	v_fma_f32 v43, -v47, v51, 1.0
	v_fmac_f32_e32 v51, v43, v51
	v_mul_f32_e32 v44, 0xbfb8aa3b, v38
	v_exp_f32_e32 v44, v44
	v_exp_f32_e32 v45, v45
	v_rcp_f32_e32 v43, v42
	s_nop 0
	v_mul_f32_e32 v36, v36, v43
	v_pk_add_f32 v[44:45], v[44:45], 1.0 op_sel_hi:[1,0]
	v_pk_mul_f32 v[32:33], v[32:33], v[36:37]
	v_div_scale_f32 v47, s[30:31], v45, v45, v39
	v_rcp_f32_e32 v50, v47
	v_cvt_pk_bf16_f32 v36, v32, v33
	v_fma_f32 v32, -v47, v50, 1.0
	v_fmac_f32_e32 v50, v32, v50
	v_div_scale_f32 v37, s[30:31], v44, v44, v38
	v_rcp_f32_e32 v42, v37
	v_rcp_f32_e32 v32, v45
	s_nop 0
	v_mul_f32_e32 v33, v39, v32
	v_fma_f32 v32, -v37, v42, 1.0
	v_fmac_f32_e32 v42, v32, v42
	v_div_scale_f32 v32, vcc, v38, v44, v38
	v_mul_f32_e32 v39, v32, v42
	v_fma_f32 v43, -v37, v39, v32
	v_rcp_f32_e32 v32, v44
	s_nop 0
	v_mul_f32_e32 v32, v38, v32
	v_pk_mul_f32 v[32:33], v[34:35], v[32:33]
	s_nop 0
	v_cvt_pk_bf16_f32 v37, v32, v33
	v_mad_i64_i32 v[32:33], s[30:31], v46, s53, v[120:121]
	v_lshl_add_u64 v[32:33], v[32:33], 0, v[122:123]
	flat_store_dwordx2 v[32:33], v[36:37]
	v_mul_f32_e32 v34, 0xbfb8aa3b, v28
	v_mul_f32_e32 v35, 0xbfb8aa3b, v29
	v_exp_f32_e32 v34, v34
	v_exp_f32_e32 v35, v35
	s_nop 0
	v_pk_add_f32 v[34:35], v[34:35], 1.0 op_sel_hi:[1,0]
	s_nop 0
	v_div_scale_f32 v38, s[30:31], v34, v34, v28
	v_rcp_f32_e32 v42, v38
	v_rcp_f32_e32 v36, v35
	s_nop 0
	v_mul_f32_e32 v29, v29, v36
	v_mul_f32_e32 v37, 0xbfb8aa3b, v31
	v_fma_f32 v35, -v38, v42, 1.0
	v_fmac_f32_e32 v42, v35, v42
	v_mul_f32_e32 v36, 0xbfb8aa3b, v30
	v_exp_f32_e32 v36, v36
	v_exp_f32_e32 v37, v37
	v_rcp_f32_e32 v35, v34
	s_nop 0
	v_mul_f32_e32 v28, v28, v35
	v_pk_add_f32 v[36:37], v[36:37], 1.0 op_sel_hi:[1,0]
	v_pk_mul_f32 v[24:25], v[24:25], v[28:29]
	v_div_scale_f32 v38, s[30:31], v37, v37, v31
	v_rcp_f32_e32 v39, v38
	v_cvt_pk_bf16_f32 v24, v24, v25
	v_div_scale_f32 v34, s[30:31], v36, v36, v30
	v_fma_f32 v25, -v38, v39, 1.0
	v_fmac_f32_e32 v39, v25, v39
	v_rcp_f32_e32 v35, v34
	v_rcp_f32_e32 v25, v37
	s_nop 0
	v_mul_f32_e32 v29, v31, v25
	v_fma_f32 v25, -v34, v35, 1.0
	v_fmac_f32_e32 v35, v25, v35
	v_div_scale_f32 v25, vcc, v30, v36, v30
	v_mul_f32_e32 v28, v25, v35
	v_fma_f32 v31, -v34, v28, v25
	v_rcp_f32_e32 v25, v36
	s_nop 0
	v_mul_f32_e32 v28, v30, v25
	v_pk_mul_f32 v[26:27], v[26:27], v[28:29]
	s_nop 0
	v_cvt_pk_bf16_f32 v25, v26, v27
	flat_store_dwordx2 v[56:57], v[24:25] offset:128
	v_mul_f32_e32 v24, 0xbfb8aa3b, v20
	v_mul_f32_e32 v25, 0xbfb8aa3b, v21
	v_exp_f32_e32 v24, v24
	v_exp_f32_e32 v25, v25
	s_nop 0
	v_pk_add_f32 v[24:25], v[24:25], 1.0 op_sel_hi:[1,0]
	s_nop 0
	v_div_scale_f32 v28, s[30:31], v24, v24, v20
	v_rcp_f32_e32 v30, v28
	v_rcp_f32_e32 v26, v25
	s_nop 0
	v_mul_f32_e32 v21, v21, v26
	v_mul_f32_e32 v27, 0xbfb8aa3b, v23
	v_fma_f32 v25, -v28, v30, 1.0
	v_fmac_f32_e32 v30, v25, v30
	v_mul_f32_e32 v26, 0xbfb8aa3b, v22
	v_exp_f32_e32 v26, v26
	v_exp_f32_e32 v27, v27
	v_rcp_f32_e32 v25, v24
	s_nop 0
	v_mul_f32_e32 v20, v20, v25
	v_pk_add_f32 v[26:27], v[26:27], 1.0 op_sel_hi:[1,0]
	v_pk_mul_f32 v[16:17], v[16:17], v[20:21]
	v_div_scale_f32 v28, s[30:31], v27, v27, v23
	v_rcp_f32_e32 v29, v28
	v_cvt_pk_bf16_f32 v16, v16, v17
	v_div_scale_f32 v24, s[30:31], v26, v26, v22
	v_fma_f32 v17, -v28, v29, 1.0
	v_fmac_f32_e32 v29, v17, v29
	v_rcp_f32_e32 v25, v24
	v_rcp_f32_e32 v17, v27
	s_nop 0
	v_mul_f32_e32 v21, v23, v17
	v_fma_f32 v17, -v24, v25, 1.0
	v_fmac_f32_e32 v25, v17, v25
	v_div_scale_f32 v17, vcc, v22, v26, v22
	v_mul_f32_e32 v20, v17, v25
	v_fma_f32 v23, -v24, v20, v17
	v_rcp_f32_e32 v17, v26
	s_nop 0
	v_mul_f32_e32 v20, v22, v17
	v_pk_mul_f32 v[18:19], v[18:19], v[20:21]
	s_nop 0
	v_cvt_pk_bf16_f32 v17, v18, v19
	flat_store_dwordx2 v[48:49], v[16:17] offset:128
	v_mul_f32_e32 v16, 0xbfb8aa3b, v12
	v_mul_f32_e32 v17, 0xbfb8aa3b, v13
	v_exp_f32_e32 v16, v16
	v_exp_f32_e32 v17, v17
	s_nop 0
	v_pk_add_f32 v[16:17], v[16:17], 1.0 op_sel_hi:[1,0]
	s_nop 0
	v_div_scale_f32 v20, s[30:31], v16, v16, v12
	v_rcp_f32_e32 v22, v20
	v_rcp_f32_e32 v18, v17
	s_nop 0
	v_mul_f32_e32 v13, v13, v18
	v_mul_f32_e32 v19, 0xbfb8aa3b, v15
	v_fma_f32 v17, -v20, v22, 1.0
	v_fmac_f32_e32 v22, v17, v22
	v_mul_f32_e32 v18, 0xbfb8aa3b, v14
	v_exp_f32_e32 v18, v18
	v_exp_f32_e32 v19, v19
	v_rcp_f32_e32 v17, v16
	s_nop 0
	v_mul_f32_e32 v12, v12, v17
	v_pk_add_f32 v[18:19], v[18:19], 1.0 op_sel_hi:[1,0]
	v_pk_mul_f32 v[8:9], v[8:9], v[12:13]
	v_div_scale_f32 v20, s[30:31], v19, v19, v15
	v_rcp_f32_e32 v21, v20
	v_cvt_pk_bf16_f32 v8, v8, v9
	v_div_scale_f32 v16, s[30:31], v18, v18, v14
	v_fma_f32 v9, -v20, v21, 1.0
	v_fmac_f32_e32 v21, v9, v21
	v_rcp_f32_e32 v17, v16
	v_rcp_f32_e32 v9, v19
	s_nop 0
	v_mul_f32_e32 v13, v15, v9
	v_fma_f32 v9, -v16, v17, 1.0
	v_fmac_f32_e32 v17, v9, v17
	v_div_scale_f32 v9, vcc, v14, v18, v14
	v_mul_f32_e32 v12, v9, v17
	v_fma_f32 v15, -v16, v12, v9
	v_rcp_f32_e32 v9, v18
	s_nop 0
	v_mul_f32_e32 v12, v14, v9
	v_pk_mul_f32 v[10:11], v[10:11], v[12:13]
	s_nop 0
	v_cvt_pk_bf16_f32 v9, v10, v11
	flat_store_dwordx2 v[40:41], v[8:9] offset:128
	v_mul_f32_e32 v8, 0xbfb8aa3b, v4
	v_mul_f32_e32 v9, 0xbfb8aa3b, v5
	v_exp_f32_e32 v8, v8
	v_exp_f32_e32 v9, v9
	s_nop 0
	v_pk_add_f32 v[8:9], v[8:9], 1.0 op_sel_hi:[1,0]
	s_nop 0
	v_div_scale_f32 v12, s[30:31], v8, v8, v4
	v_rcp_f32_e32 v14, v12
	v_rcp_f32_e32 v10, v9
	s_nop 0
	v_mul_f32_e32 v5, v5, v10
	v_mul_f32_e32 v11, 0xbfb8aa3b, v7
	v_fma_f32 v9, -v12, v14, 1.0
	v_fmac_f32_e32 v14, v9, v14
	v_mul_f32_e32 v10, 0xbfb8aa3b, v6
	v_exp_f32_e32 v10, v10
	v_exp_f32_e32 v11, v11
	v_rcp_f32_e32 v9, v8
	s_nop 0
	v_mul_f32_e32 v4, v4, v9
	v_pk_add_f32 v[10:11], v[10:11], 1.0 op_sel_hi:[1,0]
	v_pk_mul_f32 v[0:1], v[0:1], v[4:5]
	v_div_scale_f32 v12, s[30:31], v11, v11, v7
	v_rcp_f32_e32 v13, v12
	v_cvt_pk_bf16_f32 v0, v0, v1
	v_div_scale_f32 v8, s[30:31], v10, v10, v6
	v_fma_f32 v1, -v12, v13, 1.0
	v_fmac_f32_e32 v13, v1, v13
	v_rcp_f32_e32 v9, v8
	v_rcp_f32_e32 v1, v11
	s_nop 0
	v_mul_f32_e32 v5, v7, v1
	v_fma_f32 v1, -v8, v9, 1.0
	v_fmac_f32_e32 v9, v1, v9
	v_div_scale_f32 v1, vcc, v6, v10, v6
	v_mul_f32_e32 v4, v1, v9
	v_fma_f32 v7, -v8, v4, v1
	v_rcp_f32_e32 v1, v10
	s_nop 0
	v_mul_f32_e32 v4, v6, v1
	v_pk_mul_f32 v[2:3], v[2:3], v[4:5]
	s_nop 0
	v_cvt_pk_bf16_f32 v1, v2, v3
	flat_store_dwordx2 v[32:33], v[0:1] offset:128
	s_andn2_b64 vcc, exec, s[0:1]
	s_mov_b32 s56, s54
	s_mov_b32 s38, s55
	s_cbranch_vccz .LBB0_1809
